# plus: arrive+weight-wait seams no longer wait for the acquire at arrive (ClusterFinish covers it), barrier dropped, first weight stage loads moved after ClusterFinish
# speedup vs baseline: 1.0045x; 1.0015x over previous
.LBB0_84:
	s_or_b64 exec, exec, s[0:1]
	s_mov_b64 s[0:1], s[82:83]
	v_mov_b32_e32 v2, v0
	s_mov_b32 s18, s72
	s_mov_b32 s19, s73
	s_load_dwordx2 s[2:3], s[0:1], 0x90
	v_mov_b32_e32 v2, v0
	s_mov_b64 s[6:7], -1
	v_readfirstlane_b32 s41, v2
	s_waitcnt lgkmcnt(0)
	s_add_u32 s0, s2, 0x1000000
	s_addc_u32 s1, s3, 0
	s_lshl_b32 s4, s18, 3
	s_and_b32 s4, s4, 56
	s_bfe_u32 s5, s18, 0x30003
	s_or_b32 s4, s4, s5
	s_lshl_b32 s4, s4, 8
	s_add_u32 s4, s2, s4
	s_addc_u32 s5, s3, 0
	s_add_u32 s4, s4, 0x1028000
	s_addc_u32 s5, s5, 0
	s_cmpk_gt_i32 s18, 0x2ff
	v_cmp_eq_u32_e32 vcc, 0, v0
	s_cbranch_scc0 .LBB0_99
	s_and_saveexec_b64 s[6:7], vcc
	s_cbranch_execz .LBB0_98
	v_mov_b32_e32 v3, 0
	global_load_dword v4, v3, s[4:5] sc1
	s_waitcnt vmcnt(0)
	v_cmp_lt_u32_e32 vcc, 3, v4
	s_cbranch_vccnz .LBB0_97
	s_mov_b32 s14, 1
	s_branch .LBB0_89

.LBB0_99:
	s_and_b64 vcc, exec, s[6:7]
	s_cbranch_vccz .LBB0_132
	v_ashrrev_i32_e32 v3, 31, v2
	v_lshrrev_b32_e32 v3, 26, v3
	v_add_u32_e32 v3, v2, v3
	v_ashrrev_i32_e32 v4, 6, v3
	v_bfe_i32 v3, v2, 27, 1
	v_lshlrev_b32_e32 v5, 4, v2
	v_lshrrev_b32_e32 v3, 22, v3
	v_add_u32_e32 v3, v5, v3
	v_and_b32_e32 v3, 0xfffffc00, v3
	v_sub_u32_e32 v3, v5, v3
	v_lshrrev_b32_e32 v6, 4, v3
	v_bitop3_b32 v6, v6, v3, 32 bitop3:0x6c
	v_ashrrev_i32_e32 v7, 31, v6
	v_lshrrev_b32_e32 v7, 26, v7
	v_add_u32_e32 v7, v6, v7
	v_ashrrev_i32_e32 v8, 6, v7
	v_and_b32_e32 v7, 0xc0, v7
	v_sub_u32_e32 v6, v6, v7
	v_mov_b32_e32 v7, 1
	v_lshlrev_b32_e32 v3, 3, v4
	v_lshlrev_b32_e32 v4, 5, v4
	v_ashrrev_i16_sdwa v6, v7, sext(v6) dst_sel:DWORD dst_unused:UNUSED_PAD src0_sel:DWORD src1_sel:BYTE_0
	v_and_b32_e32 v3, -16, v3
	v_and_b32_e32 v4, 32, v4
	v_bfe_i32 v6, v6, 0, 16
	v_add_u32_e32 v5, 0x2000, v5
	v_add_u32_e32 v3, v8, v3
	v_add_lshl_u32 v4, v4, v6, 1
	v_ashrrev_i32_e32 v6, 31, v5
	v_lshlrev_b32_e32 v9, 1, v3
	v_lshrrev_b32_e32 v10, 2, v3
	v_and_b32_e32 v8, 3, v8
	s_mov_b32 s7, 0x1fffe0
	v_lshrrev_b32_e32 v6, 22, v6
	v_and_b32_e32 v9, 24, v9
	v_and_b32_e32 v10, 4, v10
	v_and_or_b32 v8, v3, s7, v8
	v_add_u32_e32 v6, v5, v6
	v_or3_b32 v8, v8, v10, v9
	v_ashrrev_i32_e32 v6, 10, v6
	v_lshl_add_u32 v154, v8, 11, v4
	v_mul_i32_i24_e32 v8, 0x400, v6
	v_sub_u32_e32 v5, v5, v8
	v_lshrrev_b32_e32 v8, 4, v5
	v_bitop3_b32 v8, v8, v5, 32 bitop3:0x6c
	v_ashrrev_i32_e32 v9, 31, v8
	v_lshrrev_b32_e32 v9, 26, v9
	v_lshlrev_b32_e32 v5, 3, v6
	v_add_u32_e32 v9, v8, v9
	s_add_u32 s8, s2, 0x200000
	v_and_b32_e32 v5, -16, v5
	v_ashrrev_i32_e32 v10, 6, v9
	s_addc_u32 s6, s3, 0
	v_add_u32_e32 v5, v10, v5
	v_and_b32_e32 v10, 3, v10
	s_ashr_i32 s20, s18, 31
	v_and_or_b32 v10, v5, s7, v10
	s_lshr_b32 s7, s20, 29
	s_add_i32 s7, s18, s7
	s_ashr_i32 s34, s41, 6
	s_ashr_i32 s12, s7, 3
	s_and_b32 s7, s7, -8
	s_and_b32 s9, s6, 0xffff
	s_lshl_b32 s6, s34, 10
	s_sub_i32 s7, s18, s7
	s_cmp_lt_i32 s7, 0
	s_movk_i32 s13, 0x61
	s_cselect_b32 s13, s13, 0x60
	s_mul_i32 s7, s7, s13
	s_add_i32 s7, s7, s12
	s_mul_hi_i32 s12, s7, 0x2aaaaaab
	s_lshr_b32 s13, s12, 31
	s_ashr_i32 s26, s12, 4
	s_add_i32 s26, s26, s13
	s_mul_i32 s12, s26, 0x60
	s_sub_i32 s27, s7, s12
	s_bfe_i32 s7, s27, 0x80000
	s_bfe_u32 s7, s7, 0x3000c
	v_and_b32_e32 v9, 0xc0, v9
	s_add_i32 s7, s27, s7
	v_sub_u32_e32 v8, v8, v9
	s_bfe_i32 s7, s7, 0x80000
	v_lshlrev_b32_e32 v6, 5, v6
	v_ashrrev_i16_sdwa v7, v7, sext(v8) dst_sel:DWORD dst_unused:UNUSED_PAD src0_sel:DWORD src1_sel:BYTE_0
	v_lshlrev_b32_e32 v8, 1, v5
	v_lshrrev_b32_e32 v9, 2, v5
	s_sext_i32_i16 s28, s7
	v_and_b32_e32 v6, 32, v6
	v_bfe_i32 v7, v7, 0, 16
	v_and_b32_e32 v8, 24, v8
	v_and_b32_e32 v9, 4, v9
	s_ashr_i32 s46, s28, 3
	s_add_i32 s21, s6, 0
	v_or3_b32 v8, v10, v9, v8
	v_add_lshl_u32 v6, v6, v7, 1
	s_mov_b32 s11, 0x20000
	s_mov_b32 s10, -1
	s_lshl_b32 s53, s46, 19
	s_add_i32 s22, s21, 0x10000
	v_lshl_add_u32 v155, v8, 11, v6
	s_add_i32 s23, s21, 0x12000
	s_add_i32 s24, s21, 0x14000
	s_or_b32 s6, s53, 0x40000
	s_add_i32 s25, s21, 0x16000
	v_cmp_eq_u32_e32 vcc, 0, v0
	s_and_saveexec_b64 s[6:7], vcc
	s_cbranch_execz .LBB0_113
	v_mov_b32_e32 v7, 0
	global_load_dword v8, v7, s[4:5] sc1
	s_waitcnt vmcnt(0)
	v_cmp_lt_u32_e32 vcc, 3, v8
	s_cbranch_vccnz .LBB0_112
	s_mov_b32 s29, 1
	s_branch .LBB0_104

.LBB0_113:
	s_or_b64 exec, exec, s[6:7]
	s_lshr_b32 s0, s28, 3
	s_lshl_b32 s0, s0, 3
	s_sub_i32 s0, s27, s0
	s_lshl_b32 s1, s26, 3
	s_sext_i32_i8 s0, s0
	s_add_i32 s51, s1, s0
	s_lshl_b32 s52, s51, 19
	s_add_u32 s12, s2, 0x3000000
	s_addc_u32 s0, s3, 0
	v_lshl_add_u32 v156, v3, 11, v4
	s_and_b32 s13, s0, 0xffff
	s_mov_b32 s15, 0x20000
	s_mov_b32 s14, -1
	s_barrier
	s_or_b32 s32, s53, 0x40000
	s_mov_b32 m0, s22
	s_nop 0
	buffer_load_dwordx4 v154, s[8:11], s53 offen lds
	s_nop 0
	s_mov_b32 m0, s23
	s_nop 0
	buffer_load_dwordx4 v155, s[8:11], s53 offen lds
	s_nop 0
	s_mov_b32 m0, s24
	s_nop 0
	buffer_load_dwordx4 v154, s[8:11], s32 offen lds
	s_nop 0
	s_mov_b32 m0, s25
	s_nop 0
	buffer_load_dwordx4 v155, s[8:11], s32 offen lds
	s_nop 0
	s_mov_b32 m0, s21
	s_nop 0
	buffer_load_dwordx4 v156, s[12:15], s52 offen lds
	v_lshl_add_u32 v157, v5, 11, v6
	s_add_i32 s27, s21, 0x2000
	s_mov_b32 m0, s27
	s_nop 0
	buffer_load_dwordx4 v157, s[12:15], s52 offen lds
	s_add_i32 s28, s21, 0x4000
	s_or_b32 s5, s52, 0x40000
	s_mov_b32 m0, s28
	s_nop 0
	buffer_load_dwordx4 v156, s[12:15], s5 offen lds
	s_ashr_i32 s4, s41, 8
	s_add_i32 s30, s21, 0x6000
	s_mov_b32 m0, s30
	s_nop 0
	buffer_load_dwordx4 v157, s[12:15], s5 offen lds
	s_cmp_eq_u32 s4, 1
	s_mov_b32 s26, 0
	s_mov_b32 s29, 0x40000
	s_cselect_b64 s[0:1], -1, 0
	s_cmp_lg_u32 s4, 1
	s_cbranch_scc1 .LBB0_115
	s_barrier

.LBB0_179:
	s_or_b64 exec, exec, s[2:3]
	s_mov_b64 s[2:3], s[82:83]
	v_mov_b32_e32 v2, v0
	s_mov_b32 s25, s72
	s_mov_b32 s26, s73
	s_load_dwordx2 s[16:17], s[2:3], 0x90
	s_load_dwordx2 s[0:1], s[2:3], 0x0
	s_load_dwordx2 s[22:23], s[2:3], 0x28
	v_mov_b32_e32 v2, 0x1000000
	v_mov_b32_e32 v210, v0
	s_waitcnt lgkmcnt(0)
	global_load_dword v224, v2, s[16:17] sc1
	s_add_u32 s20, s16, 0x1000000
	s_addc_u32 s21, s17, 0
	s_lshl_b32 s2, s25, 3
	s_and_b32 s2, s2, 56
	s_bfe_u32 s3, s25, 0x30003
	s_or_b32 s2, s2, s3
	s_lshl_b32 s2, s2, 8
	s_add_u32 s2, s16, s2
	s_addc_u32 s3, s17, 0
	s_add_u32 s2, s2, 0x1028000
	s_addc_u32 s3, s3, 0
	s_cmpk_gt_i32 s25, 0xff
	v_readfirstlane_b32 s27, v210
	s_mov_b64 s[4:5], -1
	s_cbranch_scc0 .LBB0_194
	s_and_saveexec_b64 s[4:5], s[56:57]
	s_cbranch_execz .LBB0_193
	v_mov_b32_e32 v2, 0
	global_load_dword v3, v2, s[2:3] sc1
	s_waitcnt vmcnt(0)
	v_cmp_lt_u32_e32 vcc, 11, v3
	s_cbranch_vccnz .LBB0_192
	s_mov_b32 s12, 1
	s_branch .LBB0_184

.LBB0_199:
	v_bfe_i32 v4, v210, 27, 1
	v_lshlrev_b32_e32 v2, 4, v210
	v_lshrrev_b32_e32 v4, 22, v4
	v_add_u32_e32 v4, v2, v4
	v_and_b32_e32 v4, 0xfffffc00, v4
	v_sub_u32_e32 v4, v2, v4
	v_lshrrev_b32_e32 v5, 4, v4
	v_bitop3_b32 v4, v5, v4, 32 bitop3:0x6c
	v_ashrrev_i32_e32 v3, 31, v210
	v_ashrrev_i32_e32 v6, 31, v4
	v_lshrrev_b32_e32 v3, 26, v3
	v_lshrrev_b32_e32 v6, 26, v6
	v_add_u32_e32 v3, v210, v3
	v_add_u32_e32 v6, v4, v6
	v_ashrrev_i32_e32 v3, 6, v3
	v_lshrrev_b32_e32 v7, 6, v6
	v_and_b32_e32 v6, 0xc0, v6
	v_lshlrev_b32_e32 v5, 3, v3
	v_lshlrev_b32_e32 v3, 5, v3
	v_sub_u32_e32 v4, v4, v6
	v_mov_b32_e32 v6, 1
	v_and_b32_e32 v5, 0x1ffff0, v5
	v_and_b32_e32 v3, 32, v3
	v_ashrrev_i16_sdwa v4, v6, sext(v4) dst_sel:DWORD dst_unused:UNUSED_PAD src0_sel:DWORD src1_sel:BYTE_0
	v_add_u32_sdwa v3, v3, sext(v4) dst_sel:DWORD dst_unused:UNUSED_PAD src0_sel:DWORD src1_sel:WORD_0
	v_add_lshl_u32 v4, v7, v5, 11
	v_add_u32_e32 v2, 0x2000, v2
	v_lshl_add_u32 v130, v3, 1, v4
	v_ashrrev_i32_e32 v3, 31, v2
	s_add_u32 s8, s16, 0x800000
	v_lshrrev_b32_e32 v3, 22, v3
	s_addc_u32 s5, s17, 0
	v_add_u32_e32 v3, v2, v3
	s_add_i32 s4, s6, s4
	v_ashrrev_i32_e32 v3, 10, v3
	s_ashr_i32 s6, s4, 31
	v_mul_i32_i24_e32 v4, 0x400, v3
	s_lshr_b32 s6, s6, 27
	v_sub_u32_e32 v2, v2, v4
	s_add_i32 s28, s4, s6
	v_lshrrev_b32_e32 v4, 4, v2
	s_and_b32 s6, s28, 0xffe0
	v_bitop3_b32 v2, v4, v2, 32 bitop3:0x6c
	s_sub_i32 s24, s4, s6
	v_ashrrev_i32_e32 v5, 31, v2
	s_bfe_i32 s4, s24, 0x80000
	v_lshrrev_b32_e32 v5, 26, v5
	s_bfe_u32 s4, s4, 0x3000c
	v_add_u32_e32 v5, v2, v5
	s_add_i32 s4, s24, s4
	s_ashr_i32 s19, s27, 6
	v_lshrrev_b32_e32 v7, 6, v5
	v_and_b32_e32 v5, 0xc0, v5
	s_bfe_i32 s4, s4, 0x80000
	v_lshlrev_b32_e32 v4, 3, v3
	v_lshlrev_b32_e32 v3, 5, v3
	v_sub_u32_e32 v2, v2, v5
	s_and_b32 s9, s5, 0xffff
	s_lshl_b32 s5, s19, 10
	s_sext_i32_i16 s29, s4
	v_and_b32_e32 v4, 0x1ffff0, v4
	v_and_b32_e32 v3, 32, v3
	v_ashrrev_i16_sdwa v2, v6, sext(v2) dst_sel:DWORD dst_unused:UNUSED_PAD src0_sel:DWORD src1_sel:BYTE_0
	s_ashr_i32 s18, s29, 3
	s_add_i32 s31, s5, 0
	v_add_u32_sdwa v2, v3, sext(v2) dst_sel:DWORD dst_unused:UNUSED_PAD src0_sel:DWORD src1_sel:WORD_0
	v_add_lshl_u32 v3, v7, v4, 11
	s_mov_b32 s11, 0x20000
	s_mov_b32 s10, -1
	s_lshl_b32 s34, s18, 19
	s_add_i32 s33, s31, 0x10000
	v_lshl_add_u32 v131, v2, 1, v3
	s_add_i32 s35, s31, 0x12000
	s_add_i32 s36, s31, 0x14000
	s_or_b32 s4, s34, 0x40000
	s_add_i32 s37, s31, 0x16000
	s_and_saveexec_b64 s[4:5], s[56:57]
	s_cbranch_execz .LBB0_212
	v_mov_b32_e32 v2, 0
	global_load_dword v3, v2, s[2:3] sc1
	s_waitcnt vmcnt(0)
	v_cmp_lt_u32_e32 vcc, 11, v3
	s_cbranch_vccnz .LBB0_211
	s_mov_b32 s38, 1
	s_branch .LBB0_203

.LBB0_212:
	s_or_b64 exec, exec, s[4:5]
	s_lshr_b32 s3, s29, 3
	s_lshl_b32 s3, s3, 3
	s_ashr_i32 s2, s28, 5
	s_sub_i32 s3, s24, s3
	s_lshl_b32 s2, s2, 3
	s_sext_i32_i8 s3, s3
	s_add_i32 s29, s2, s3
	s_lshl_b32 s39, s29, 19
	s_add_u32 s12, s16, 0xa800000
	s_addc_u32 s2, s17, 0
	s_and_b32 s13, s2, 0xffff
	s_mov_b32 s15, 0x20000
	s_mov_b32 s14, -1
	s_barrier
	s_or_b32 s32, s34, 0x40000
	s_mov_b32 m0, s33
	s_nop 0
	buffer_load_dwordx4 v130, s[8:11], s34 offen lds
	s_nop 0
	s_mov_b32 m0, s35
	s_nop 0
	buffer_load_dwordx4 v131, s[8:11], s34 offen lds
	s_nop 0
	s_mov_b32 m0, s36
	s_nop 0
	buffer_load_dwordx4 v130, s[8:11], s32 offen lds
	s_nop 0
	s_mov_b32 m0, s37
	s_nop 0
	buffer_load_dwordx4 v131, s[8:11], s32 offen lds
	s_nop 0
	s_mov_b32 m0, s31
	s_nop 0
	buffer_load_dwordx4 v130, s[12:15], s39 offen lds
	s_add_i32 s40, s31, 0x2000
	s_mov_b32 m0, s40
	s_nop 0
	buffer_load_dwordx4 v131, s[12:15], s39 offen lds
	s_add_i32 s41, s31, 0x4000
	s_or_b32 s2, s39, 0x40000
	s_mov_b32 m0, s41
	s_nop 0
	buffer_load_dwordx4 v130, s[12:15], s2 offen lds
	s_add_i32 s42, s31, 0x6000
	s_mov_b32 m0, s42
	s_nop 0
	buffer_load_dwordx4 v131, s[12:15], s2 offen lds
	s_ashr_i32 s24, s27, 8
	s_cmp_lg_u32 s24, 1
	s_cbranch_scc1 .LBB0_214
	s_barrier

.LBB0_417:
	s_or_b64 exec, exec, s[2:3]
	s_mov_b64 s[0:1], s[82:83]
	v_mov_b32_e32 v2, v0
	s_mov_b32 s25, s73
	s_mov_b32 s26, s72
	s_load_dwordx2 s[16:17], s[0:1], 0x90
	s_load_dwordx2 s[22:23], s[0:1], 0x48
	v_mov_b32_e32 v2, 0x1000000
	v_mov_b32_e32 v146, v0
	s_waitcnt lgkmcnt(0)
	global_load_dword v223, v2, s[16:17] sc1
	s_add_u32 s20, s16, 0x1000000
	s_addc_u32 s21, s17, 0
	s_cmpk_gt_i32 s26, 0xff
	s_cselect_b64 s[2:3], -1, 0
	s_and_b64 vcc, exec, s[2:3]
	v_readfirstlane_b32 s27, v146
	s_cbranch_vccnz .LBB0_423
	s_ashr_i32 s0, s26, 31
	s_lshr_b32 s0, s0, 29
	s_add_i32 s6, s26, s0
	s_and_b32 s0, s6, -8
	s_sub_i32 s4, s26, s0
	s_cmp_gt_i32 s4, -1
	s_cbranch_scc0 .LBB0_420
	s_lshl_b32 s5, s4, 5
	s_ashr_i32 s0, s6, 3
	s_cbranch_execz .LBB0_421
	s_branch .LBB0_422

.LBB0_438:
	s_and_b64 vcc, exec, s[2:3]
	s_cbranch_vccz .LBB0_525
	v_bfe_i32 v4, v146, 27, 1
	v_lshlrev_b32_e32 v2, 4, v146
	v_lshrrev_b32_e32 v4, 22, v4
	v_add_u32_e32 v4, v2, v4
	v_and_b32_e32 v4, 0xfffffc00, v4
	v_sub_u32_e32 v4, v2, v4
	v_ashrrev_i32_e32 v3, 31, v146
	v_lshrrev_b32_e32 v5, 4, v4
	v_lshrrev_b32_e32 v3, 26, v3
	v_bitop3_b32 v4, v5, v4, 32 bitop3:0x6c
	v_add_u32_e32 v3, v146, v3
	v_ashrrev_i32_e32 v6, 31, v4
	v_ashrrev_i32_e32 v3, 6, v3
	v_lshrrev_b32_e32 v6, 26, v6
	v_lshlrev_b32_e32 v5, 3, v3
	v_add_u32_e32 v6, v4, v6
	v_and_b32_e32 v5, 0xfffff0, v5
	v_lshrrev_b32_e32 v7, 6, v6
	v_and_b32_e32 v6, 0xc0, v6
	v_add_u32_e32 v5, v7, v5
	v_sub_u32_e32 v4, v4, v6
	v_mov_b32_e32 v6, 1
	s_movk_i32 s3, 0xb00
	v_lshlrev_b32_e32 v3, 5, v3
	v_ashrrev_i16_sdwa v4, v6, sext(v4) dst_sel:DWORD dst_unused:UNUSED_PAD src0_sel:DWORD src1_sel:BYTE_0
	v_mul_lo_u32 v5, v5, s3
	v_bfe_i32 v4, v4, 0, 16
	v_and_or_b32 v3, v3, 32, v5
	v_add_u32_e32 v2, 0x2000, v2
	v_add_lshl_u32 v130, v3, v4, 1
	v_ashrrev_i32_e32 v3, 31, v2
	v_lshrrev_b32_e32 v3, 22, v3
	v_add_u32_e32 v3, v2, v3
	v_ashrrev_i32_e32 v3, 10, v3
	v_mul_i32_i24_e32 v4, 0x400, v3
	v_sub_u32_e32 v2, v2, v4
	v_lshrrev_b32_e32 v4, 4, v2
	v_bitop3_b32 v2, v4, v2, 32 bitop3:0x6c
	v_ashrrev_i32_e32 v5, 31, v2
	v_lshrrev_b32_e32 v5, 26, v5
	s_add_u32 s8, s16, 0x2000000
	v_lshlrev_b32_e32 v4, 3, v3
	v_add_u32_e32 v5, v2, v5
	s_addc_u32 s2, s17, 0
	s_ashr_i32 s19, s27, 6
	v_and_b32_e32 v4, 0xfffff0, v4
	v_lshrrev_b32_e32 v7, 6, v5
	v_and_b32_e32 v5, 0xc0, v5
	v_add_u32_e32 v4, v7, v4
	v_sub_u32_e32 v2, v2, v5
	s_and_b32 s9, s2, 0xffff
	s_lshl_b32 s2, s19, 10
	v_lshlrev_b32_e32 v3, 5, v3
	v_ashrrev_i16_sdwa v2, v6, sext(v2) dst_sel:DWORD dst_unused:UNUSED_PAD src0_sel:DWORD src1_sel:BYTE_0
	v_mul_lo_u32 v4, v4, s3
	s_add_i32 s28, s2, 0
	v_bfe_i32 v2, v2, 0, 16
	v_and_or_b32 v3, v3, 32, v4
	s_mov_b32 s11, 0x20000
	s_mov_b32 s10, -1
	s_mul_i32 s33, s18, 0x160000
	s_add_i32 s29, s28, 0x10000
	v_add_lshl_u32 v131, v3, v2, 1
	s_add_i32 s34, s28, 0x12000
	s_add_i32 s35, s28, 0x14000
	s_add_i32 s2, s33, 0xb0000
	s_add_i32 s36, s28, 0x16000
	s_and_saveexec_b64 s[2:3], s[56:57]
	s_cbranch_execz .LBB0_452
	v_mov_b32_e32 v2, 0
	global_load_dword v3, v2, s[0:1] sc1
	s_waitcnt vmcnt(0)
	v_cmp_lt_u32_e32 vcc, 23, v3
	s_cbranch_vccnz .LBB0_451
	s_mov_b32 s14, 1
	s_branch .LBB0_443

.LBB0_452:
	s_or_b64 exec, exec, s[2:3]
	s_add_u32 s12, s16, 0x5000000
	s_addc_u32 s0, s17, 0
	s_mul_i32 s3, s31, 0x160000
	s_and_b32 s13, s0, 0xffff
	s_mov_b32 s15, 0x20000
	s_mov_b32 s14, -1
	s_barrier
	s_add_i32 s32, s33, 0xb0000
	s_mov_b32 m0, s29
	s_nop 0
	buffer_load_dwordx4 v130, s[8:11], s33 offen lds
	s_nop 0
	s_mov_b32 m0, s34
	s_nop 0
	buffer_load_dwordx4 v131, s[8:11], s33 offen lds
	s_nop 0
	s_mov_b32 m0, s35
	s_nop 0
	buffer_load_dwordx4 v130, s[8:11], s32 offen lds
	s_nop 0
	s_mov_b32 m0, s36
	s_nop 0
	buffer_load_dwordx4 v131, s[8:11], s32 offen lds
	s_nop 0
	s_mov_b32 m0, s28
	s_nop 0
	buffer_load_dwordx4 v130, s[12:15], s3 offen lds
	s_add_i32 s37, s28, 0x2000
	s_mov_b32 m0, s37
	s_nop 0
	buffer_load_dwordx4 v131, s[12:15], s3 offen lds
	s_add_i32 s38, s28, 0x4000
	s_add_i32 s0, s3, 0xb0000
	s_mov_b32 m0, s38
	s_nop 0
	buffer_load_dwordx4 v130, s[12:15], s0 offen lds
	s_add_i32 s39, s28, 0x6000
	s_mov_b32 m0, s39
	s_nop 0
	buffer_load_dwordx4 v131, s[12:15], s0 offen lds
	s_ashr_i32 s24, s27, 8
	s_cmp_lg_u32 s24, 1
	s_cbranch_scc1 .LBB0_454
	s_barrier

.LBB0_577:
	s_or_b64 exec, exec, s[2:3]
	s_mov_b64 s[22:23], s[82:83]
	v_mov_b32_e32 v183, v0
	s_mov_b32 s45, s73
	s_mov_b32 s43, s72
	s_load_dwordx2 s[20:21], s[22:23], 0x90
	s_cmpk_gt_i32 s43, 0x17f
	v_mov_b32_e32 v2, v0
	s_cselect_b64 s[4:5], -1, 0
	v_readfirstlane_b32 s42, v183
	s_and_b64 vcc, exec, s[4:5]
	v_readfirstlane_b32 s36, v2
	s_cbranch_vccnz .LBB0_579
	s_ashr_i32 s0, s43, 31
	s_lshr_b32 s0, s0, 29
	s_add_i32 s0, s43, s0
	s_ashr_i32 s1, s0, 3
	s_and_b32 s0, s0, -8
	s_sub_i32 s0, s43, s0
	s_cmp_lt_i32 s0, 0
	s_cselect_b32 s2, 49, 48
	s_mul_i32 s0, s0, s2
	s_add_i32 s0, s0, s1
	s_mul_hi_i32 s1, s0, 0x2aaaaaab
	s_lshr_b32 s2, s1, 31
	s_ashr_i32 s1, s1, 3
	s_add_i32 s1, s1, s2
	s_lshl_b32 s2, s1, 3
	s_mul_i32 s1, s1, 48
	s_sub_i32 s0, s0, s1
	s_bfe_i32 s1, s0, 0x80000
	s_bfe_u32 s1, s1, 0x3000c
	s_add_i32 s1, s0, s1
	s_bfe_i32 s3, s1, 0x80000
	s_and_b32 s1, s1, 0xf8
	s_sub_i32 s0, s0, s1
	s_sext_i32_i16 s3, s3
	s_sext_i32_i8 s0, s0
	s_add_i32 s40, s2, s0
	s_ashr_i32 s33, s3, 3

.LBB0_590:
	s_and_b64 vcc, exec, s[4:5]
	s_cbranch_vccz .LBB0_605
	v_ashrrev_i32_e32 v3, 31, v2
	v_lshrrev_b32_e32 v3, 26, v3
	v_add_u32_e32 v3, v2, v3
	v_ashrrev_i32_e32 v4, 6, v3
	v_bfe_i32 v3, v2, 27, 1
	v_lshlrev_b32_e32 v5, 4, v2
	v_lshrrev_b32_e32 v3, 22, v3
	v_add_u32_e32 v3, v5, v3
	v_and_b32_e32 v3, 0xfffffc00, v3
	v_sub_u32_e32 v3, v5, v3
	v_lshrrev_b32_e32 v6, 4, v3
	v_bitop3_b32 v6, v6, v3, 32 bitop3:0x6c
	v_ashrrev_i32_e32 v7, 31, v6
	v_lshrrev_b32_e32 v7, 26, v7
	v_add_u32_e32 v7, v6, v7
	v_ashrrev_i32_e32 v8, 6, v7
	v_and_b32_e32 v7, 0xc0, v7
	v_sub_u32_e32 v6, v6, v7
	v_mov_b32_e32 v7, 1
	v_lshlrev_b32_e32 v3, 3, v4
	v_lshlrev_b32_e32 v4, 5, v4
	v_ashrrev_i16_sdwa v6, v7, sext(v6) dst_sel:DWORD dst_unused:UNUSED_PAD src0_sel:DWORD src1_sel:BYTE_0
	v_and_b32_e32 v3, -16, v3
	v_and_b32_e32 v4, 32, v4
	v_bfe_i32 v6, v6, 0, 16
	v_add_u32_e32 v5, 0x2000, v5
	v_add_u32_e32 v3, v8, v3
	v_add_lshl_u32 v4, v4, v6, 1
	v_ashrrev_i32_e32 v6, 31, v5
	v_lshlrev_b32_e32 v9, 1, v3
	v_lshrrev_b32_e32 v10, 2, v3
	v_and_b32_e32 v8, 3, v8
	s_mov_b32 s5, 0x3fffe0
	v_lshrrev_b32_e32 v6, 22, v6
	v_and_b32_e32 v9, 24, v9
	v_and_b32_e32 v10, 4, v10
	v_and_or_b32 v8, v3, s5, v8
	v_add_u32_e32 v6, v5, v6
	v_or3_b32 v8, v8, v10, v9
	v_ashrrev_i32_e32 v6, 10, v6
	v_lshl_add_u32 v204, v8, 10, v4
	v_mul_i32_i24_e32 v8, 0x400, v6
	v_sub_u32_e32 v5, v5, v8
	v_lshrrev_b32_e32 v8, 4, v5
	v_bitop3_b32 v8, v8, v5, 32 bitop3:0x6c
	v_ashrrev_i32_e32 v9, 31, v8
	v_lshrrev_b32_e32 v9, 26, v9
	v_lshlrev_b32_e32 v5, 3, v6
	v_add_u32_e32 v9, v8, v9
	s_add_u32 s12, s20, 0x2b00000
	v_and_b32_e32 v5, -16, v5
	v_ashrrev_i32_e32 v10, 6, v9
	v_and_b32_e32 v9, 0xc0, v9
	s_addc_u32 s4, s21, 0
	s_ashr_i32 s34, s36, 6
	v_add_u32_e32 v5, v10, v5
	v_sub_u32_e32 v8, v8, v9
	v_lshlrev_b32_e32 v6, 5, v6
	v_ashrrev_i16_sdwa v7, v7, sext(v8) dst_sel:DWORD dst_unused:UNUSED_PAD src0_sel:DWORD src1_sel:BYTE_0
	v_lshlrev_b32_e32 v8, 1, v5
	v_lshrrev_b32_e32 v9, 2, v5
	v_and_b32_e32 v10, 3, v10
	s_and_b32 s13, s4, 0xffff
	s_lshl_b32 s4, s34, 10
	v_and_b32_e32 v6, 32, v6
	v_bfe_i32 v7, v7, 0, 16
	v_and_b32_e32 v8, 24, v8
	v_and_b32_e32 v9, 4, v9
	v_and_or_b32 v10, v5, s5, v10
	s_add_i32 s47, s4, 0
	v_or3_b32 v8, v10, v9, v8
	v_add_lshl_u32 v6, v6, v7, 1
	s_mov_b32 s15, 0x20000
	s_mov_b32 s14, -1
	s_lshl_b32 s41, s33, 18
	s_add_i32 s48, s47, 0x10000
	v_lshl_add_u32 v205, v8, 10, v6
	s_add_i32 s49, s47, 0x12000
	s_add_i32 s50, s47, 0x14000
	s_or_b32 s4, s41, 0x20000
	s_add_i32 s51, s47, 0x16000
	s_and_saveexec_b64 s[4:5], s[56:57]
	s_cbranch_execz .LBB0_609
	v_mov_b32_e32 v7, 0
	global_load_dword v8, v7, s[2:3] sc1
	s_waitcnt vmcnt(0)
	v_cmp_lt_u32_e32 vcc, 31, v8
	s_cbranch_vccnz .LBB0_608
	s_mov_b32 s16, 1
	s_branch .LBB0_595

.LBB0_609:
	s_or_b64 exec, exec, s[4:5]
	s_add_u32 s16, s20, 0x5000000
	s_addc_u32 s1, s21, 0
	s_mul_i32 s2, s40, 0x160000
	v_lshl_add_u32 v206, v3, 10, v4
	s_and_b32 s17, s1, 0xffff
	s_mov_b32 s19, 0x20000
	s_mov_b32 s18, -1
	s_barrier
	s_or_b32 s32, s41, 0x20000
	s_mov_b32 m0, s48
	s_nop 0
	buffer_load_dwordx4 v204, s[12:15], s41 offen lds
	s_nop 0
	s_mov_b32 m0, s49
	s_nop 0
	buffer_load_dwordx4 v205, s[12:15], s41 offen lds
	s_nop 0
	s_mov_b32 m0, s50
	s_nop 0
	buffer_load_dwordx4 v204, s[12:15], s32 offen lds
	s_nop 0
	s_mov_b32 m0, s51
	s_nop 0
	buffer_load_dwordx4 v205, s[12:15], s32 offen lds
	s_nop 0
	s_mov_b32 m0, s47
	s_nop 0
	buffer_load_dwordx4 v206, s[16:19], s2 offen lds
	v_lshl_add_u32 v207, v5, 10, v6
	s_add_i32 s52, s47, 0x2000
	s_mov_b32 m0, s52
	s_nop 0
	buffer_load_dwordx4 v207, s[16:19], s2 offen lds
	s_add_i32 s53, s47, 0x4000
	s_add_i32 s1, s2, 0x20000
	s_mov_b32 m0, s53
	s_nop 0
	buffer_load_dwordx4 v206, s[16:19], s1 offen lds
	s_ashr_i32 s0, s36, 8
	s_add_i32 s54, s47, 0x6000
	s_mov_b32 m0, s54
	s_nop 0
	buffer_load_dwordx4 v207, s[16:19], s1 offen lds
	s_cmp_eq_u32 s0, 1
	s_mov_b32 s80, s73
	s_mov_b32 s77, s72
	s_mov_b32 s11, 0
	s_cselect_b64 s[24:25], -1, 0
	s_cmp_lg_u32 s0, 1
	s_cbranch_scc1 .LBB0_611
	s_barrier

.LBB0_899:
	s_or_b64 exec, exec, s[2:3]
	s_mov_b64 s[0:1], s[82:83]
	v_mov_b32_e32 v2, v0
	s_mov_b32 s24, s72
	s_mov_b32 s25, s73
	s_load_dwordx2 s[16:17], s[0:1], 0x90
	s_load_dwordx2 s[22:23], s[0:1], 0x80
	v_mov_b32_e32 v2, 0x1000000
	v_mov_b32_e32 v241, v0
	s_mov_b64 s[2:3], -1
	s_waitcnt lgkmcnt(0)
	global_load_dword v239, v2, s[16:17] sc1
	s_add_u32 s20, s16, 0x1000000
	s_addc_u32 s21, s17, 0
	s_lshl_b32 s0, s24, 3
	s_and_b32 s0, s0, 56
	s_bfe_u32 s1, s24, 0x30003
	s_or_b32 s0, s0, s1
	s_lshl_b32 s0, s0, 8
	s_add_u32 s0, s16, s0
	s_addc_u32 s1, s17, 0
	s_add_u32 s0, s0, 0x1028000
	s_addc_u32 s1, s1, 0
	s_cmpk_gt_i32 s24, 0xff
	v_readfirstlane_b32 s26, v241
	s_cbranch_scc0 .LBB0_914
	s_and_saveexec_b64 s[2:3], s[56:57]
	s_cbranch_execz .LBB0_913
	v_mov_b32_e32 v2, 0
	global_load_dword v3, v2, s[0:1] sc1
	s_waitcnt vmcnt(0)
	v_cmp_lt_u32_e32 vcc, 39, v3
	s_cbranch_vccnz .LBB0_912
	s_mov_b32 s10, 1
	s_branch .LBB0_904

.LBB0_919:
	v_bfe_i32 v4, v241, 27, 1
	v_lshlrev_b32_e32 v2, 4, v241
	v_lshrrev_b32_e32 v4, 22, v4
	v_add_u32_e32 v4, v2, v4
	v_and_b32_e32 v4, 0xfffffc00, v4
	v_sub_u32_e32 v4, v2, v4
	v_lshrrev_b32_e32 v5, 4, v4
	v_bitop3_b32 v4, v5, v4, 32 bitop3:0x6c
	v_ashrrev_i32_e32 v3, 31, v241
	v_ashrrev_i32_e32 v6, 31, v4
	v_lshrrev_b32_e32 v3, 26, v3
	v_lshrrev_b32_e32 v6, 26, v6
	v_add_u32_e32 v3, v241, v3
	v_add_u32_e32 v6, v4, v6
	v_ashrrev_i32_e32 v3, 6, v3
	v_lshrrev_b32_e32 v7, 6, v6
	v_and_b32_e32 v6, 0xc0, v6
	v_lshlrev_b32_e32 v5, 3, v3
	v_lshlrev_b32_e32 v3, 5, v3
	v_sub_u32_e32 v4, v4, v6
	v_mov_b32_e32 v8, 1
	v_and_b32_e32 v5, 0x3ffff0, v5
	v_and_b32_e32 v3, 32, v3
	v_ashrrev_i16_sdwa v4, v8, sext(v4) dst_sel:DWORD dst_unused:UNUSED_PAD src0_sel:DWORD src1_sel:BYTE_0
	v_add_u32_sdwa v3, v3, sext(v4) dst_sel:DWORD dst_unused:UNUSED_PAD src0_sel:DWORD src1_sel:WORD_0
	v_add_lshl_u32 v4, v7, v5, 10
	v_add_u32_e32 v2, 0x2000, v2
	v_lshl_add_u32 v6, v3, 1, v4
	v_ashrrev_i32_e32 v3, 31, v2
	s_add_u32 s8, s16, 0x2e00000
	v_lshrrev_b32_e32 v3, 22, v3
	s_addc_u32 s3, s17, 0
	v_add_u32_e32 v3, v2, v3
	s_add_i32 s2, s4, s2
	v_ashrrev_i32_e32 v3, 10, v3
	s_ashr_i32 s4, s2, 31
	v_mul_i32_i24_e32 v4, 0x400, v3
	s_lshr_b32 s4, s4, 27
	v_sub_u32_e32 v2, v2, v4
	s_add_i32 s15, s2, s4
	v_lshrrev_b32_e32 v4, 4, v2
	s_and_b32 s4, s15, 0xffe0
	v_bitop3_b32 v2, v4, v2, 32 bitop3:0x6c
	s_sub_i32 s14, s2, s4
	v_ashrrev_i32_e32 v5, 31, v2
	s_bfe_i32 s2, s14, 0x80000
	v_lshrrev_b32_e32 v5, 26, v5
	s_bfe_u32 s2, s2, 0x3000c
	v_add_u32_e32 v5, v2, v5
	s_add_i32 s2, s14, s2
	s_ashr_i32 s19, s26, 6
	v_lshrrev_b32_e32 v7, 6, v5
	v_and_b32_e32 v5, 0xc0, v5
	s_bfe_i32 s2, s2, 0x80000
	v_lshlrev_b32_e32 v4, 3, v3
	v_lshlrev_b32_e32 v3, 5, v3
	v_sub_u32_e32 v2, v2, v5
	s_and_b32 s9, s3, 0xffff
	s_lshl_b32 s3, s19, 10
	s_sext_i32_i16 s30, s2
	v_and_b32_e32 v4, 0x3ffff0, v4
	v_and_b32_e32 v3, 32, v3
	v_ashrrev_i16_sdwa v2, v8, sext(v2) dst_sel:DWORD dst_unused:UNUSED_PAD src0_sel:DWORD src1_sel:BYTE_0
	s_ashr_i32 s18, s30, 3
	s_add_i32 s28, s3, 0
	v_add_u32_sdwa v2, v3, sext(v2) dst_sel:DWORD dst_unused:UNUSED_PAD src0_sel:DWORD src1_sel:WORD_0
	v_add_lshl_u32 v3, v7, v4, 10
	s_mov_b32 s11, 0x20000
	s_mov_b32 s10, -1
	s_lshl_b32 s33, s18, 18
	s_add_i32 s29, s28, 0x10000
	v_lshl_add_u32 v7, v2, 1, v3
	s_add_i32 s34, s28, 0x12000
	s_add_i32 s35, s28, 0x14000
	s_or_b32 s2, s33, 0x20000
	s_add_i32 s36, s28, 0x16000
	s_and_saveexec_b64 s[2:3], s[56:57]
	s_cbranch_execz .LBB0_932
	v_mov_b32_e32 v2, 0
	global_load_dword v3, v2, s[0:1] sc1
	s_waitcnt vmcnt(0)
	v_cmp_lt_u32_e32 vcc, 39, v3
	s_cbranch_vccnz .LBB0_931
	s_mov_b32 s31, 1
	s_branch .LBB0_923

.LBB0_932:
	s_or_b64 exec, exec, s[2:3]
	s_lshr_b32 s1, s30, 3
	s_lshl_b32 s1, s1, 3
	s_ashr_i32 s0, s15, 5
	s_sub_i32 s1, s14, s1
	s_lshl_b32 s0, s0, 3
	s_sext_i32_i8 s1, s1
	s_add_i32 s31, s0, s1
	s_lshl_b32 s37, s31, 19
	s_add_u32 s12, s16, 0xdc00000
	s_addc_u32 s0, s17, 0
	s_and_b32 s13, s0, 0xffff
	s_mov_b32 s15, 0x20000
	s_mov_b32 s14, -1
	s_barrier
	s_or_b32 s32, s33, 0x20000
	s_mov_b32 m0, s29
	s_nop 0
	buffer_load_dwordx4 v6, s[8:11], s33 offen lds
	s_nop 0
	s_mov_b32 m0, s34
	s_nop 0
	buffer_load_dwordx4 v7, s[8:11], s33 offen lds
	s_nop 0
	s_mov_b32 m0, s35
	s_nop 0
	buffer_load_dwordx4 v6, s[8:11], s32 offen lds
	s_nop 0
	s_mov_b32 m0, s36
	s_nop 0
	buffer_load_dwordx4 v7, s[8:11], s32 offen lds
	s_nop 0
	s_mov_b32 m0, s28
	s_nop 0
	buffer_load_dwordx4 v6, s[12:15], s37 offen lds
	s_add_i32 s38, s28, 0x2000
	s_mov_b32 m0, s38
	s_nop 0
	buffer_load_dwordx4 v7, s[12:15], s37 offen lds
	s_add_i32 s40, s28, 0x4000
	s_or_b32 s0, s37, 0x20000
	s_mov_b32 m0, s40
	s_nop 0
	buffer_load_dwordx4 v6, s[12:15], s0 offen lds
	s_add_i32 s41, s28, 0x6000
	s_mov_b32 m0, s41
	s_nop 0
	buffer_load_dwordx4 v7, s[12:15], s0 offen lds
	s_ashr_i32 s2, s26, 8
	s_mov_b32 s39, 0
	s_cmp_lg_u32 s2, 1
	s_cbranch_scc1 .LBB0_934
	s_barrier
